# conv2d quarter-task balancing with a generic-grid fallback path
# baseline (speedup 1.0000x reference)
.LBB0_928:
	s_cmp_lt_i32 s76, 12
	s_cselect_b64 s[16:17], -1, 0
	s_and_b64 s[4:5], s[16:17], s[46:47]
	s_andn2_b64 vcc, exec, s[4:5]
	s_cbranch_vccnz .LBB0_979
	s_and_b32 s4, s2, 7
	s_mulk_i32 s4, 0x2c0
	s_and_b32 s5, s2, -8
	s_and_b32 s3, s38, 7
	s_lshl_b32 s10, s2, 3
	s_add_i32 s11, s4, s5
	s_add_i32 s12, s4, 0x2c0
	s_cmp_eq_u32 s3, 0
	s_cselect_b64 s[6:7], -1, 0
	s_and_b64 s[4:5], s[6:7], exec
	s_cselect_b32 s3, s11, s10
	s_waitcnt vmcnt(0)
	v_add_u32_e32 v166, s3, v197
	s_cselect_b32 s27, s12, 0x1600
	s_mov_b64 s[8:9], s[0:1]
	s_movk_i32 s3, 0x1600
	v_readfirstlane_b32 s92, v197
	s_and_b32 s93, s2, 7
	s_mulk_i32 s93, 0x2c0
	s_and_b32 s99, s2, -8
	s_add_u32 s92, s92, s99
	v_readfirstlane_b32 s95, v166
	s_mov_b32 s98, 0
	v_cmp_gt_i32_e32 vcc, s27, v166
	s_and_saveexec_b64 s[18:19], vcc
	s_cbranch_execz .LBB0_978
	s_load_dwordx4 s[12:15], s[8:9], 0xb8
	s_load_dwordx2 s[20:21], s[8:9], 0xe0
	s_and_b32 s10, s38, -8
	s_lshl_b32 s11, s38, 3
	s_and_b64 s[4:5], s[6:7], exec
	s_cselect_b32 s29, s10, s11
	s_waitcnt lgkmcnt(0)
	s_add_u32 s22, s20, 0xd200e00
	v_lshlrev_b32_e32 v0, 2, v196
	s_addc_u32 s23, s21, 0
	v_and_b32_e32 v167, 0xfc, v0
	s_mov_b64 s[24:25], 0
	s_mov_b32 s39, 0x2e8ba2e9
	s_movk_i32 s48, 0x2000
	s_movk_i32 s49, 0x5000
	s_mov_b32 s50, 0x8000
	s_mov_b32 s51, 0xb000
	s_mov_b32 s52, 0xd000
	s_mov_b32 s53, 0x10000
	s_mov_b32 s54, 0x13000
	s_mov_b32 s55, 0x16000
	s_movk_i32 s56, 0x7c
	s_mov_b32 s57, 0x2c00000
	v_mov_b64_e32 v[40:41], s[22:23]
	s_movk_i32 s58, 0x80
	v_mov_b32_e32 v42, 0
	s_movk_i32 s59, 0x100
	s_mov_b32 s60, 0x160000
	s_mov_b32 s61, 0x23200000
	s_mov_b32 s26, 0x3dd2d3e7
	s_mov_b32 s28, 0xc0135761
	s_mov_b32 s62, 0x23202000
	s_mov_b32 s63, 0x23203000
	s_mov_b32 s88, s61
	s_mov_b32 s89, 0
	s_mov_b32 s90, s63
	s_mov_b32 s91, 0
	s_branch .LBB0_932

.LBB0_932:
	s_cmp_eq_u32 s38, 0x100
	s_cbranch_scc0 .Lq_generic
	s_cmp_lt_u32 s98, 5
	s_cbranch_scc0 .LBB0_978
	s_cmp_lt_u32 s98, 2
	s_cbranch_scc0 .Lq_quarter
	s_lshl_b32 s99, s98, 8
	s_add_u32 s99, s99, s92
	s_add_u32 s99, s99, s93
	s_mov_b32 s100, 0
	s_mov_b32 s101, 32
	s_branch .Lq_set
.Lq_quarter:
	s_mul_i32 s99, s92, 3
	s_add_u32 s99, s99, s98
	s_sub_u32 s99, s99, 2
	s_and_b32 s100, s99, 3
	s_lshl_b32 s100, s100, 3
	s_lshr_b32 s99, s99, 2
	s_add_u32 s99, s99, 0x200
	s_add_u32 s99, s99, s93
	s_mov_b32 s101, 8
	s_branch .Lq_set
.Lq_generic:
	s_mul_i32 s99, s98, s29
	s_add_u32 s99, s99, s95
	s_cmp_ge_i32 s99, s27
	s_cbranch_scc1 .LBB0_978
	s_mov_b32 s100, 0
	s_mov_b32 s101, 32
